# plus: warm loads also in the W_glu / W_o transpose loops (phase-1 light blocks)
# speedup vs baseline: 1.0354x; 1.0009x over previous
; DEVINL void tr_tile(const Params& p, char* smem, int kind, int nt, int kt) {
;     ...
;   } else if (kind == 1) {
;     src = p.w_glu; ld = 512; col = n; K = 512; dst = (u16*)(p.ws + OFF_WGLUT);
;   } else if (kind == 2) {
;     src = p.w_o; ld = 1024; col = n; dst = (u16*)(p.ws + OFF_WOT);
;     ...
;   __syncthreads();
; #pragma unroll 4
;   for (int i = 0; i < 16; ++i) {
;     int k = kq * 16 + i;
;     float v = valid ? src[(size_t)(k0 + k) * ld + col] : 0.f;
;     if (ksc) v *= ksc[k0 + k];
;     if (kind == 2 && (k0 + k) >= 512) v *= p.s5_norm[k0 + k - 512];
;     T[k * 65 + nl] = v * cs;
;   }
.LBB0_1441:
	v_cmp_lt_i32_e32 vcc, 63, v16
	s_and_saveexec_b64 s[0:1], vcc
	s_xor_b64 s[38:39], exec, s[0:1]
	s_cbranch_execz .LBB0_1453
	v_mov_b32_e32 v3, v0
	s_waitcnt lgkmcnt(0)
	v_and_b32_e32 v4, 0x3c0, v18
	v_ashrrev_i32_e32 v1, 2, v3
	s_waitcnt lgkmcnt(0)
	v_and_b32_e32 v5, -16, v1
	v_lshrrev_b32_e32 v6, 4, v1
	s_movk_i32 s0, 0x1040
	v_add_u32_e32 v4, v4, v5
	v_and_b32_e32 v8, 63, v3
	v_mul_lo_u32 v6, v6, s0
	v_ashrrev_i32_e32 v5, 31, v4
	s_mov_b32 s0, 0x7fffffc0
	v_lshl_add_u32 v10, v8, 2, v6
	v_lshlrev_b64 v[6:7], 12, v[4:5]
	v_and_or_b32 v5, v20, s0, v8
	v_add_u32_e32 v8, 0xffffff00, v5
	v_mov_b32_e32 v9, v2
	v_readlane_b32 s0, v192, 31
	v_lshl_add_u64 v[6:7], v[8:9], 2, v[6:7]
	v_readlane_b32 s1, v192, 32
	v_mov_b32_e32 v5, v2
	s_mov_b32 s14, 0
	v_lshl_add_u64 v[6:7], s[0:1], 0, v[6:7]
	v_readlane_b32 s0, v192, 33
	v_readlane_b32 s1, v192, 34
	s_barrier
	s_nop 0
	v_lshl_add_u64 v[8:9], v[4:5], 2, s[0:1]
	s_mov_b32 s100, 0xffffd000
	s_mov_b32 s101, -1
	v_lshl_add_u64 v[206:207], v[6:7], 0, s[100:101]
	s_mov_b64 s[100:101], 0x1000
	global_load_dword v204, v[206:207], off
	v_lshl_add_u64 v[206:207], v[206:207], 0, s[100:101]
	global_load_dword v204, v[206:207], off
	v_lshl_add_u64 v[206:207], v[206:207], 0, s[100:101]
	global_load_dword v204, v[206:207], off
	v_lshl_add_u64 v[206:207], v[206:207], 0, s[100:101]
	global_load_dword v204, v[206:207], off
	v_lshl_add_u64 v[206:207], v[206:207], 0, s[100:101]
	global_load_dword v204, v[206:207], off
	v_lshl_add_u64 v[206:207], v[206:207], 0, s[100:101]
	global_load_dword v204, v[206:207], off
	v_lshl_add_u64 v[206:207], v[206:207], 0, s[100:101]
	global_load_dword v204, v[206:207], off
	v_lshl_add_u64 v[206:207], v[206:207], 0, s[100:101]
	global_load_dword v204, v[206:207], off
	v_lshl_add_u64 v[206:207], v[206:207], 0, s[100:101]
	global_load_dword v204, v[206:207], off
	v_lshl_add_u64 v[206:207], v[206:207], 0, s[100:101]
	global_load_dword v204, v[206:207], off
	v_lshl_add_u64 v[206:207], v[206:207], 0, s[100:101]
	global_load_dword v204, v[206:207], off
	v_lshl_add_u64 v[206:207], v[206:207], 0, s[100:101]
	global_load_dword v204, v[206:207], off
	v_lshl_add_u64 v[206:207], v[206:207], 0, s[100:101]
	global_load_dword v204, v[206:207], off
	v_lshl_add_u64 v[206:207], v[206:207], 0, s[100:101]
	global_load_dword v204, v[206:207], off
	v_lshl_add_u64 v[206:207], v[206:207], 0, s[100:101]
	global_load_dword v204, v[206:207], off
	v_lshl_add_u64 v[206:207], v[206:207], 0, s[100:101]
	global_load_dword v204, v[206:207], off
	s_branch .LBB0_1444

; DEVINL void tr_tile(const Params& p, char* smem, int kind, int nt, int kt) {
;     ...
;   } else if (kind == 1) {
;     src = p.w_glu; ld = 512; col = n; K = 512; dst = (u16*)(p.ws + OFF_WGLUT);
;     ...
;   __syncthreads();
; #pragma unroll 4
;   for (int i = 0; i < 16; ++i) {
;     int k = kq * 16 + i;
;     float v = valid ? src[(size_t)(k0 + k) * ld + col] : 0.f;
;     if (ksc) v *= ksc[k0 + k];
;     if (kind == 2 && (k0 + k) >= 512) v *= p.s5_norm[k0 + k - 512];
;     T[k * 65 + nl] = v * cs;
;   }
.LBB0_1453:
	s_andn2_saveexec_b64 s[38:39], s[38:39]
	s_cbranch_execz .LBB0_1440
	v_ashrrev_i32_e32 v1, 31, v16
	v_lshrrev_b32_e32 v1, 29, v1
	v_add_u32_e32 v1, v16, v1
	v_and_b32_e32 v3, 0x3fffff8, v1
	v_mov_b32_e32 v7, v0
	v_lshlrev_b32_e32 v1, 3, v1
	v_sub_u32_e32 v3, v16, v3
	v_lshlrev_b32_e32 v12, 6, v3
	s_waitcnt lgkmcnt(0)
	v_bfi_b32 v4, 63, v7, v1
	v_ashrrev_i32_e32 v15, 2, v7
	v_and_b32_e32 v3, 63, v7
	s_waitcnt lgkmcnt(0)
	v_ashrrev_i32_e32 v5, 31, v4
	v_and_b32_e32 v8, -16, v15
	v_and_b32_e32 v13, 0xffffffc0, v1
	v_lshl_add_u64 v[4:5], v[4:5], 2, s[10:11]
	v_lshlrev_b32_e32 v6, 2, v3
	v_mov_b32_e32 v1, v12
	v_mov_b32_e32 v3, v8
	s_mov_b32 s0, 1
	s_mov_b32 s1, 0
	s_mov_b32 s14, 16
	s_barrier
	v_add_u32_e32 v206, v8, v12
	v_ashrrev_i32_e32 v207, 31, v206
	v_lshlrev_b64 v[206:207], 11, v[206:207]
	v_lshl_add_u64 v[206:207], v[4:5], 0, v[206:207]
	s_mov_b64 s[100:101], 0x800
	global_load_dword v204, v[206:207], off
	v_lshl_add_u64 v[206:207], v[206:207], 0, s[100:101]
	global_load_dword v204, v[206:207], off
	v_lshl_add_u64 v[206:207], v[206:207], 0, s[100:101]
	global_load_dword v204, v[206:207], off
	v_lshl_add_u64 v[206:207], v[206:207], 0, s[100:101]
	global_load_dword v204, v[206:207], off
	v_lshl_add_u64 v[206:207], v[206:207], 0, s[100:101]
	global_load_dword v204, v[206:207], off
	v_lshl_add_u64 v[206:207], v[206:207], 0, s[100:101]
	global_load_dword v204, v[206:207], off
	v_lshl_add_u64 v[206:207], v[206:207], 0, s[100:101]
	global_load_dword v204, v[206:207], off
	v_lshl_add_u64 v[206:207], v[206:207], 0, s[100:101]
	global_load_dword v204, v[206:207], off
	v_lshl_add_u64 v[206:207], v[206:207], 0, s[100:101]
	global_load_dword v204, v[206:207], off
	v_lshl_add_u64 v[206:207], v[206:207], 0, s[100:101]
	global_load_dword v204, v[206:207], off
	v_lshl_add_u64 v[206:207], v[206:207], 0, s[100:101]
	global_load_dword v204, v[206:207], off
	v_lshl_add_u64 v[206:207], v[206:207], 0, s[100:101]
	global_load_dword v204, v[206:207], off
	v_lshl_add_u64 v[206:207], v[206:207], 0, s[100:101]
	global_load_dword v204, v[206:207], off
	v_lshl_add_u64 v[206:207], v[206:207], 0, s[100:101]
	global_load_dword v204, v[206:207], off
	v_lshl_add_u64 v[206:207], v[206:207], 0, s[100:101]
	global_load_dword v204, v[206:207], off
	v_lshl_add_u64 v[206:207], v[206:207], 0, s[100:101]
	global_load_dword v204, v[206:207], off
